# MLA: early waves issue staging DMAs inside their P.V MFMA run (late waves inside P.V(prev)); softmax denominator as 4 add chains; spurious vmcnt(0) in in-proj/qkv epilogues removed
# speedup vs baseline: 1.0003x; 1.0003x over previous
; DI u32x4 pack8(f32x4 a, f32x4 b) { u32x4 o; o.x = pk2(a.x, a.y); o.y = pk2(a.z, a.w); o.z = pk2(b.x, b.y); o.w = pk2(b.z, b.w); return o; }
; DI float sq4(f32x4 v) { return (v.x * v.x + v.y * v.y) + (v.z * v.z + v.w * v.w); }
; DI float xhalf_sum(float x) { float lo, hi; xhalf(x, lo, hi); return lo + hi; }
;     DI void operator()(AccT& acc, const Unit& u, int wr, int wc, int fr, int fq) const {
;     ...
;                 for (int bj = 0; bj < 2; ++bj) {
;                     f32x4 v0 = acc[ai][bj][m][0] * rs, v1 = acc[ai][bj][m][1] * rs;
;                     const int cl = bj * 128 + wc * 32 + fq * 8;
;                     if (do_rope && bj == 1) rope8(v0, v1, rca[ai * 4 + m], rcb[ai * 4 + m]);
;                     if (pn == 6 || (pn == 7 && bj == 0)) ss += sq4(v0) + sq4(v1);
;                     if (pn == 4 || pn == 5) {
;                         const int dg = (pn - 4) * 256 + cl, hd = dg >> 6, d = dg & 63, b = row >> 12, s = row & 4095;
;                         store_tr8(vst + ((size_t)(b * 8 + hd) * 64 + d) * S_ + s, v0, v1);
;                     } else {
;                         *(u32x4*)(proj + (size_t)row * 2048 + pn * 256 + cl) = pack8(v0, v1);
;                     }
;                 }
;                 if (pn >= 6) { ss += __shfl_xor(ss, 16); ss = xhalf_sum(ss); if (fq == 0) (pn == 6 ? pq : pkv)[(size_t)row * 4 + wc] = ss; }
.LBB0_199:
	v_mul_f32_e32 v152, v235, v235
	v_mul_f32_e32 v153, v231, v231
	v_fmac_f32_e32 v152, v234, v234
	v_fmac_f32_e32 v153, v230, v230
	v_add_f32_e32 v152, v152, v153
	v_mul_f32_e32 v153, v233, v233
	v_mul_f32_e32 v154, v229, v229
	s_cmp_eq_u32 s8, 6
	v_fmac_f32_e32 v153, v232, v232
	v_fmac_f32_e32 v154, v228, v228
	s_cselect_b64 s[38:39], -1, 0
	s_cmp_eq_u32 s12, 6
	v_add_f32_e32 v153, v153, v154
	s_cselect_b64 s[6:7], -1, 0
	s_cmp_lg_u32 s8, 6
	v_add_f32_e32 v152, v152, v153
	s_cbranch_scc1 .LBB0_201
	v_mov_b32_e32 v184, v171
	v_mov_b32_e32 v185, v169
	v_mov_b32_e32 v154, v170
	v_mov_b32_e32 v155, v168
	v_pk_mul_f32 v[184:185], v[184:185], v[184:185]
	v_mov_b32_e32 v186, v157
	v_mov_b32_e32 v187, v159
	v_pk_fma_f32 v[154:155], v[154:155], v[154:155], v[184:185]
	v_mov_b32_e32 v184, v156
	v_mov_b32_e32 v185, v158
	v_pk_mul_f32 v[186:187], v[186:187], v[186:187]
	s_nop 0
	v_pk_fma_f32 v[184:185], v[184:185], v[184:185], v[186:187]
	s_nop 0
	v_pk_add_f32 v[154:155], v[154:155], v[184:185]
	s_nop 0
	v_add_f32_e32 v153, v154, v155
	v_add_f32_e32 v184, v152, v153
	s_branch .LBB0_202
.LBB0_201:
	v_cndmask_b32_e64 v184, 0, v152, s[6:7]

; DI u32x4 pack8(f32x4 a, f32x4 b) { u32x4 o; o.x = pk2(a.x, a.y); o.y = pk2(a.z, a.w); o.z = pk2(b.x, b.y); o.w = pk2(b.z, b.w); return o; }
;     DI void operator()(AccT& acc, const Unit& u, int wr, int wc, int fr, int fq) const {
;     ...
;                     const int hd = pn - 3;
;                     const int cl = wc * 32 + fq * 8, b = row >> 12, s = row & 4095;
;                     { f32x4 v0 = acc[ai][0][m][0] * rs, v1 = acc[ai][0][m][1] * rs; *(u32x4*)(kn + (size_t)row * 512 + hd * 128 + cl) = pack8(v0, v1); }
;                     { f32x4 v0 = acc[ai][1][m][0] * rs, v1 = acc[ai][1][m][1] * rs; store_tr8(vmt + ((size_t)(b * 4 + hd) * 128 + cl) * S_ + s, v0, v1); }
.LBB0_408:
	v_lshl_add_u64 v[184:185], v[212:213], 1, v[222:223]
	s_mov_b64 s[28:29], 0
	global_store_dwordx4 v[184:185], v[192:195], off offset:256
.LBB0_409:
	s_ashr_i32 s2, s17, 10
	s_add_i32 s21, s12, -3
	s_and_b32 s2, s2, -4
	s_add_i32 s2, s2, s21
	s_ashr_i32 s3, s2, 31
	s_lshl_b32 s12, s21, 7
	v_lshlrev_b64 v[184:185], 13, v[212:213]
	s_lshl_b64 s[2:3], s[2:3], 20
	s_and_b64 vcc, exec, s[28:29]
	s_cbranch_vccz .LBB0_411
	s_waitcnt lgkmcnt(0)
	v_pk_mul_f32 v[168:169], v[168:169], v[220:221] op_sel_hi:[1,0]
	v_pk_mul_f32 v[186:187], v[166:167], v[220:221] op_sel_hi:[1,0]
	v_pk_mul_f32 v[166:167], v[164:165], v[220:221] op_sel_hi:[1,0]
	v_cvt_pk_bf16_f32 v164, v168, v169
	v_lshlrev_b64 v[168:169], 10, v[218:219]
	v_lshl_add_u64 v[168:169], s[10:11], 0, v[168:169]
	v_pk_mul_f32 v[170:171], v[170:171], v[220:221] op_sel_hi:[1,0]
	v_lshl_add_u64 v[168:169], s[12:13], 1, v[168:169]
	s_add_u32 s26, s39, s2
	v_and_b32_e32 v188, 0xfff, v218
	v_cvt_pk_bf16_f32 v165, v170, v171
	v_cvt_pk_bf16_f32 v166, v166, v167
	v_cvt_pk_bf16_f32 v167, v186, v187
	v_lshl_add_u64 v[168:169], v[212:213], 1, v[168:169]
	s_addc_u32 s27, s40, s3
	global_store_dwordx4 v[168:169], v[164:167], off
	v_pk_mul_f32 v[170:171], v[176:177], v[220:221] op_sel_hi:[1,0]
	v_lshl_add_u64 v[176:177], s[26:27], 0, v[184:185]
	v_pk_mul_f32 v[166:167], v[180:181], v[220:221] op_sel_hi:[1,0]
	v_lshlrev_b32_e32 v208, 1, v188
	v_lshl_add_u64 v[176:177], v[176:177], 0, v[208:209]
	v_cvt_pk_bf16_f32 v166, v166, v167
	global_store_short v[176:177], v166, off
	v_add_co_u32_e32 v166, vcc, s50, v176
	v_pk_mul_f32 v[168:169], v[178:179], v[220:221] op_sel_hi:[1,0]
	v_cvt_pk_bf16_f32 v178, v167, s0
	v_addc_co_u32_e32 v167, vcc, 0, v177, vcc
	v_pk_mul_f32 v[164:165], v[182:183], v[220:221] op_sel_hi:[1,0]
	global_store_short v[166:167], v178, off
	v_add_co_u32_e32 v166, vcc, s51, v176
	v_cvt_pk_bf16_f32 v164, v164, v165
	s_nop 0
	v_addc_co_u32_e32 v167, vcc, 0, v177, vcc
	global_store_short v[166:167], v164, off
	v_add_co_u32_e32 v164, vcc, s52, v176
	v_cvt_pk_bf16_f32 v166, v165, s0
	s_nop 0
	v_addc_co_u32_e32 v165, vcc, 0, v177, vcc
	global_store_short v[164:165], v166, off
	v_add_co_u32_e32 v164, vcc, s45, v176
	v_cvt_pk_bf16_f32 v166, v170, v171
	s_nop 0
	v_addc_co_u32_e32 v165, vcc, 0, v177, vcc
	global_store_short v[164:165], v166, off
	v_add_co_u32_e32 v164, vcc, s46, v176
	v_cvt_pk_bf16_f32 v166, v171, s0
	s_nop 0
	v_addc_co_u32_e32 v165, vcc, 0, v177, vcc
	global_store_short v[164:165], v166, off
	v_add_co_u32_e32 v164, vcc, 0xc000, v176
	v_cvt_pk_bf16_f32 v166, v168, v169
	s_nop 0
	v_addc_co_u32_e32 v165, vcc, 0, v177, vcc
	global_store_short v[164:165], v166, off
	v_add_co_u32_e32 v164, vcc, 0xe000, v176
	v_cvt_pk_bf16_f32 v166, v169, s0
	s_nop 0
	v_addc_co_u32_e32 v165, vcc, 0, v177, vcc
	global_store_short v[164:165], v166, off

; #define LAS __attribute__((address_space(3)))
; DI f32x16 zero16() { f32x16 z; for (int i = 0; i < 16; ++i) z[i] = 0.f; return z; }
; #define MFMA32(a, b, c) __builtin_amdgcn_mfma_f32_32x32x16_bf16((a), (b), (c), 0, 0, 0)
; DI void mla_s_softmax(const LAS unsigned char* base, int r, int h, bool is_diag, int lim, const bf16x8 (&qf)[12], f32x16 (&o)[4], float& m_run, float& l_run,
;                       bf16x8 (&pf0)[2], bf16x8 (&pf1)[2]) {
;     f32x16 s0 = zero16(), s1 = zero16();
;     const LAS unsigned char* kp = base + r * MLA_KROW + h * 16;
; #pragma unroll
;     for (int g = 0; g < 3; ++g) {
;         bf16x8 fa[4], fb[4];
; #pragma unroll
;         for (int j = 0; j < 4; ++j) { fa[j] = *(const LAS bf16x8*)(kp + (4 * g + j) * 32); fb[j] = *(const LAS bf16x8*)(kp + 32 * MLA_KROW + (4 * g + j) * 32); }
;         __builtin_amdgcn_sched_barrier(0);
; #pragma unroll
;         for (int j = 0; j < 4; ++j) { s0 = MFMA32(fa[j], qf[4 * g + j], s0); s1 = MFMA32(fb[j], qf[4 * g + j], s1); }
;         __builtin_amdgcn_sched_barrier(0);
;     }
.LBB0_639:
	s_add_i32 s73, s89, 0
	v_add3_u32 v0, s73, v174, v162
	s_andn2_b64 vcc, exec, s[2:3]
	s_branch .Lmla_splain_0
	s_cmp_ge_u32 s88, s74
	s_cbranch_scc1 .Lmla_splain_0
	s_mul_i32 s91, s76, 0xac00
	ds_read_b128 v[2:5], v0
	ds_read_b128 v[6:9], v0 offset:32
	ds_read_b128 v[10:13], v0 offset:12800
	ds_read_b128 v[186:189], v0 offset:12832
	ds_read_b128 v[190:193], v0 offset:64
	ds_read_b128 v[194:197], v0 offset:96
	ds_read_b128 v[198:201], v0 offset:12864
	ds_read_b128 v[202:205], v0 offset:12896
	ds_read_b128 v[206:209], v0 offset:128
	ds_read_b128 v[210:213], v0 offset:160
	ds_read_b128 v[214:217], v0 offset:12928
	ds_read_b128 v[218:221], v0 offset:12960
	ds_read_b128 v[222:225], v0 offset:192
	ds_read_b128 v[226:229], v0 offset:224
	ds_read_b128 v[230:233], v0 offset:12992
	ds_read_b128 v[234:237], v0 offset:13024
	s_waitcnt lgkmcnt(8)
	v_mfma_f32_32x32x16_bf16 v[96:111], v[2:5], v[112:115], 0
	v_readlane_b32 s90, v255, 11
	v_lshl_add_u32 v253, s88, v176, v166
	s_add_i32 m0, s91, s90
	s_nop 0
	global_load_lds_dwordx4 v253, s[12:13]
	v_mfma_f32_32x32x16_bf16 v[80:95], v[10:13], v[112:115], 0
	v_mfma_f32_32x32x16_bf16 v[96:111], v[6:9], v[116:119], v[96:111]
	v_lshl_add_u32 v253, s88, v177, v167
	s_add_i32 m0, s91, s85
	s_nop 0
	global_load_lds_dwordx4 v253, s[12:13]
	v_mfma_f32_32x32x16_bf16 v[80:95], v[186:189], v[116:119], v[80:95]
	v_mfma_f32_32x32x16_bf16 v[96:111], v[190:193], v[120:123], v[96:111]
	v_lshl_add_u32 v253, s88, v178, v168
	s_add_i32 m0, s91, s72
	s_nop 0
	global_load_lds_dwordx4 v253, s[12:13]
	v_mfma_f32_32x32x16_bf16 v[80:95], v[198:201], v[120:123], v[80:95]
	v_mfma_f32_32x32x16_bf16 v[96:111], v[194:197], v[124:127], v[96:111]
	v_lshl_add_u32 v253, s88, v179, v169
	s_add_i32 m0, s91, s75
	s_nop 0
	global_load_lds_dwordx4 v253, s[12:13]
	v_mfma_f32_32x32x16_bf16 v[80:95], v[202:205], v[124:127], v[80:95]
	ds_read_b128 v[2:5], v0 offset:256
	ds_read_b128 v[6:9], v0 offset:288
	ds_read_b128 v[10:13], v0 offset:13056
	ds_read_b128 v[186:189], v0 offset:13088
	ds_read_b128 v[190:193], v0 offset:320
	ds_read_b128 v[194:197], v0 offset:352
	ds_read_b128 v[198:201], v0 offset:13120
	ds_read_b128 v[202:205], v0 offset:13152
	s_waitcnt lgkmcnt(8)
	v_mfma_f32_32x32x16_bf16 v[96:111], v[206:209], v[128:131], v[96:111]
	v_lshl_add_u32 v253, s88, v180, v170
	s_add_i32 m0, s91, s1
	s_nop 0
	global_load_lds_dwordx4 v253, s[12:13]
	v_mfma_f32_32x32x16_bf16 v[80:95], v[214:217], v[128:131], v[80:95]
	v_mfma_f32_32x32x16_bf16 v[96:111], v[210:213], v[132:135], v[96:111]
	s_andn2_b64 vcc, exec, s[94:95]
	s_cbranch_vccnz .Lmla_a5_s_0
	v_readlane_b32 s90, v255, 9
	v_lshl_add_u32 v253, s88, v181, v171
	s_add_i32 m0, s91, s90
	s_nop 0
	global_load_lds_dwordx4 v253, s[12:13]

; #define LAS __attribute__((address_space(3)))
; DI unsigned pk2(float lo, float hi) { f32x2 v = {lo, hi}; bf2_t r = __builtin_convertvector(v, bf2_t); return __builtin_bit_cast(unsigned, r); }
; #define MFMA32(a, b, c) __builtin_amdgcn_mfma_f32_32x32x16_bf16((a), (b), (c), 0, 0, 0)
; DI void mla_s_softmax(const LAS unsigned char* base, int r, int h, bool is_diag, int lim, const bf16x8 (&qf)[12], f32x16 (&o)[4], float& m_run, float& l_run,
;                       bf16x8 (&pf0)[2], bf16x8 (&pf1)[2]) {
;     ...
;     float ls = 0.f;
; #pragma unroll
;     for (int i = 0; i < 16; ++i) { s0[i] = __builtin_amdgcn_exp2f(s0[i] - m_run); s1[i] = __builtin_amdgcn_exp2f(s1[i] - m_run); ls += s0[i] + s1[i]; }
;     l_run += ls;
; #pragma unroll
;     for (int s = 0; s < 2; ++s) {
;         u32x4 a, c;
;         a.x = pk2(s0[8 * s + 0], s0[8 * s + 1]); a.y = pk2(s0[8 * s + 2], s0[8 * s + 3]); a.z = pk2(s0[8 * s + 4], s0[8 * s + 5]); a.w = pk2(s0[8 * s + 6], s0[8 * s + 7]);
;         c.x = pk2(s1[8 * s + 0], s1[8 * s + 1]); c.y = pk2(s1[8 * s + 2], s1[8 * s + 3]); c.z = pk2(s1[8 * s + 4], s1[8 * s + 5]); c.w = pk2(s1[8 * s + 6], s1[8 * s + 7]);
;         pf0[s] = __builtin_bit_cast(bf16x8, a); pf1[s] = __builtin_bit_cast(bf16x8, c);
;     }
; }
; DI void mla_pv(const LAS unsigned char* base, int r, int h, const bf16x8 (&pf0)[2], const bf16x8 (&pf1)[2], f32x16 (&o)[4]) {
;     const LAS unsigned char* vp = base + MLA_KBYTES + r * MLA_VROW + h * 32;
; #pragma unroll
;     for (int s = 0; s < 2; ++s) {
;         bf16x8 va[4], vb[4];
; #pragma unroll
;         for (int dt = 0; dt < 4; ++dt) { va[dt] = *(const LAS bf16x8*)(vp + dt * 32 * MLA_VROW + s * 16); vb[dt] = *(const LAS bf16x8*)(vp + dt * 32 * MLA_VROW + 64 + s * 16); }
;         __builtin_amdgcn_sched_barrier(0);
; #pragma unroll
;         for (int dt = 0; dt < 4; ++dt) o[dt] = MFMA32(va[dt], pf0[s], o[dt]);
; #pragma unroll
;         for (int dt = 0; dt < 4; ++dt) o[dt] = MFMA32(vb[dt], pf1[s], o[dt]);
;         __builtin_amdgcn_sched_barrier(0);
;     }
.LBB0_643:
	v_sub_f32_e32 v0, v96, v183
	v_exp_f32_e32 v15, v0
	v_sub_f32_e32 v0, v80, v183
	v_sub_f32_e32 v2, v98, v183
	v_exp_f32_e32 v185, v0
	v_sub_f32_e32 v0, v97, v183
	v_exp_f32_e32 v97, v2
	v_sub_f32_e32 v2, v82, v183
	v_exp_f32_e32 v187, v2
	v_sub_f32_e32 v2, v99, v183
	v_exp_f32_e32 v96, v2
	v_sub_f32_e32 v2, v83, v183
	v_exp_f32_e32 v98, v2
	v_sub_f32_e32 v2, v100, v183
	v_exp_f32_e32 v186, v2
	v_sub_f32_e32 v2, v84, v183
	v_exp_f32_e32 v189, v2
	v_sub_f32_e32 v2, v101, v183
	v_exp_f32_e32 v84, v2
	v_sub_f32_e32 v2, v85, v183
	v_exp_f32_e32 v100, v2
	v_sub_f32_e32 v2, v102, v183
	v_exp_f32_e32 v188, v2
	v_sub_f32_e32 v2, v86, v183
	v_exp_f32_e32 v191, v2
	v_sub_f32_e32 v2, v103, v183
	v_exp_f32_e32 v86, v2
	v_sub_f32_e32 v2, v87, v183
	v_exp_f32_e32 v102, v2
	v_sub_f32_e32 v2, v104, v183
	v_exp_f32_e32 v190, v2
	v_sub_f32_e32 v2, v88, v183
	v_exp_f32_e32 v193, v2
	v_sub_f32_e32 v2, v105, v183
	v_exp_f32_e32 v88, v2
	v_sub_f32_e32 v2, v89, v183
	v_exp_f32_e32 v104, v2
	v_sub_f32_e32 v2, v106, v183
	v_exp_f32_e32 v192, v2
	v_sub_f32_e32 v2, v90, v183
	v_exp_f32_e32 v195, v2
	v_sub_f32_e32 v2, v107, v183
	v_exp_f32_e32 v90, v2
	v_sub_f32_e32 v2, v91, v183
	v_exp_f32_e32 v106, v2
	v_sub_f32_e32 v2, v108, v183
	v_exp_f32_e32 v194, v2
	v_sub_f32_e32 v2, v92, v183
	v_exp_f32_e32 v197, v2
	v_sub_f32_e32 v2, v109, v183
	v_exp_f32_e32 v92, v2
	v_sub_f32_e32 v2, v93, v183
	v_exp_f32_e32 v108, v2
	v_sub_f32_e32 v2, v110, v183
	v_exp_f32_e32 v196, v2
	v_sub_f32_e32 v2, v94, v183
	v_exp_f32_e32 v198, v2
	v_sub_f32_e32 v2, v111, v183
	v_exp_f32_e32 v14, v0
	v_sub_f32_e32 v0, v81, v183
	v_exp_f32_e32 v94, v2
	v_sub_f32_e32 v2, v95, v183
	v_exp_f32_e32 v0, v0
	v_exp_f32_e32 v110, v2
	v_cvt_pk_bf16_f32 v80, v15, v14
	v_cvt_pk_bf16_f32 v81, v97, v96
	v_cvt_pk_bf16_f32 v82, v186, v84
	v_cvt_pk_bf16_f32 v83, v188, v86
	v_cvt_pk_bf16_f32 v6, v185, v0
	v_cvt_pk_bf16_f32 v7, v187, v98
	v_cvt_pk_bf16_f32 v8, v189, v100
	v_cvt_pk_bf16_f32 v9, v191, v102
	v_cvt_pk_bf16_f32 v10, v190, v88
	v_cvt_pk_bf16_f32 v11, v192, v90
	v_cvt_pk_bf16_f32 v12, v194, v92
	v_cvt_pk_bf16_f32 v13, v196, v94
	v_cvt_pk_bf16_f32 v2, v193, v104
	v_cvt_pk_bf16_f32 v3, v195, v106
	v_cvt_pk_bf16_f32 v4, v197, v108
	s_andn2_b64 vcc, exec, s[2:3]
	v_cvt_pk_bf16_f32 v5, v198, v110
	s_cbranch_vccnz .LBB0_645
	s_cmp_ge_u32 s88, s74
	s_cbranch_scc1 .Lmla_epv_plain_0
	s_mul_i32 s91, s76, 0xac00
	s_waitcnt lgkmcnt(0)
	v_mfma_f32_32x32x16_bf16 v[64:79], v[200:203], v[80:83], v[64:79]
	v_readlane_b32 s90, v255, 11
	v_lshl_add_u32 v253, s88, v176, v166
	s_add_i32 m0, s91, s90
	s_nop 0
	global_load_lds_dwordx4 v253, s[12:13]
	v_mfma_f32_32x32x16_bf16 v[48:63], v[208:211], v[80:83], v[48:63]
	v_mfma_f32_32x32x16_bf16 v[32:47], v[216:219], v[80:83], v[32:47]
	v_lshl_add_u32 v253, s88, v177, v167
	s_add_i32 m0, s91, s85
	s_nop 0
	global_load_lds_dwordx4 v253, s[12:13]
	v_mfma_f32_32x32x16_bf16 v[16:31], v[224:227], v[80:83], v[16:31]
	v_mfma_f32_32x32x16_bf16 v[64:79], v[204:207], v[6:9], v[64:79]
	v_lshl_add_u32 v253, s88, v178, v168
	s_add_i32 m0, s91, s72
	s_nop 0
	global_load_lds_dwordx4 v253, s[12:13]
	v_mfma_f32_32x32x16_bf16 v[48:63], v[212:215], v[6:9], v[48:63]
	v_mfma_f32_32x32x16_bf16 v[32:47], v[220:223], v[6:9], v[32:47]
	v_lshl_add_u32 v253, s88, v179, v169
	s_add_i32 m0, s91, s75
	s_nop 0
	global_load_lds_dwordx4 v253, s[12:13]
	v_mfma_f32_32x32x16_bf16 v[16:31], v[228:231], v[6:9], v[16:31]
	ds_read_b128 v[200:203], v252 offset:30288
	ds_read_b128 v[204:207], v252 offset:34896
	ds_read_b128 v[208:211], v252 offset:39504
	v_mfma_f32_32x32x16_bf16 v[64:79], v[232:235], v[10:13], v[64:79]
	v_lshl_add_u32 v253, s88, v180, v170
	s_add_i32 m0, s91, s1
	s_nop 0
	global_load_lds_dwordx4 v253, s[12:13]
	v_mfma_f32_32x32x16_bf16 v[48:63], v[236:239], v[10:13], v[48:63]
	v_mfma_f32_32x32x16_bf16 v[32:47], v[240:243], v[10:13], v[32:47]
	s_andn2_b64 vcc, exec, s[94:95]
	s_cbranch_vccnz .Lmla_a5_epv_0
	v_readlane_b32 s90, v255, 9
	v_lshl_add_u32 v253, s88, v181, v171
	s_add_i32 m0, s91, s90
	s_nop 0
	global_load_lds_dwordx4 v253, s[12:13]
.Lmla_a5_epv_0:
	v_mfma_f32_32x32x16_bf16 v[16:31], v[244:247], v[10:13], v[16:31]
	v_mfma_f32_32x32x16_bf16 v[64:79], v[248:251], v[2:5], v[64:79]
	s_waitcnt lgkmcnt(0)
	v_mfma_f32_32x32x16_bf16 v[48:63], v[200:203], v[2:5], v[48:63]
	v_mfma_f32_32x32x16_bf16 v[32:47], v[204:207], v[2:5], v[32:47]
	v_mfma_f32_32x32x16_bf16 v[16:31], v[208:211], v[2:5], v[16:31]
	s_branch .LBB0_645
.Lmla_epv_plain_0:
	s_waitcnt lgkmcnt(0)
	v_mfma_f32_32x32x16_bf16 v[64:79], v[200:203], v[80:83], v[64:79]
	v_mfma_f32_32x32x16_bf16 v[48:63], v[208:211], v[80:83], v[48:63]
	v_mfma_f32_32x32x16_bf16 v[32:47], v[216:219], v[80:83], v[32:47]
	v_mfma_f32_32x32x16_bf16 v[16:31], v[224:227], v[80:83], v[16:31]
	v_mfma_f32_32x32x16_bf16 v[64:79], v[204:207], v[6:9], v[64:79]
	v_mfma_f32_32x32x16_bf16 v[48:63], v[212:215], v[6:9], v[48:63]
	v_mfma_f32_32x32x16_bf16 v[32:47], v[220:223], v[6:9], v[32:47]
	v_mfma_f32_32x32x16_bf16 v[16:31], v[228:231], v[6:9], v[16:31]
	ds_read_b128 v[200:203], v252 offset:30288
	ds_read_b128 v[204:207], v252 offset:34896
	ds_read_b128 v[208:211], v252 offset:39504
	v_mfma_f32_32x32x16_bf16 v[64:79], v[232:235], v[10:13], v[64:79]
	v_mfma_f32_32x32x16_bf16 v[48:63], v[236:239], v[10:13], v[48:63]
	v_mfma_f32_32x32x16_bf16 v[32:47], v[240:243], v[10:13], v[32:47]
	v_mfma_f32_32x32x16_bf16 v[16:31], v[244:247], v[10:13], v[16:31]
	v_mfma_f32_32x32x16_bf16 v[64:79], v[248:251], v[2:5], v[64:79]
	s_waitcnt lgkmcnt(0)
	v_mfma_f32_32x32x16_bf16 v[48:63], v[200:203], v[2:5], v[48:63]
	v_mfma_f32_32x32x16_bf16 v[32:47], v[204:207], v[2:5], v[32:47]
	v_mfma_f32_32x32x16_bf16 v[16:31], v[208:211], v[2:5], v[16:31]
.LBB0_645:
	v_add_f32_e32 v85, v15, v185
	v_add_f32_e32 v87, v14, v0
	v_add_f32_e32 v89, v97, v187
	v_add_f32_e32 v91, v96, v98
	v_add_f32_e32 v85, v85, v186
	v_add_f32_e32 v87, v87, v189
	v_add_f32_e32 v89, v89, v84
	v_add_f32_e32 v91, v91, v100
	v_add_f32_e32 v85, v85, v188
	v_add_f32_e32 v87, v87, v191
	v_add_f32_e32 v89, v89, v86
	v_add_f32_e32 v91, v91, v102
	v_add_f32_e32 v85, v85, v190
	v_add_f32_e32 v87, v87, v193
	v_add_f32_e32 v89, v89, v88
	v_add_f32_e32 v91, v91, v104
	v_add_f32_e32 v85, v85, v192
	v_add_f32_e32 v87, v87, v195
	v_add_f32_e32 v89, v89, v90
	v_add_f32_e32 v91, v91, v106
	v_add_f32_e32 v85, v85, v194
	v_add_f32_e32 v87, v87, v197
	v_add_f32_e32 v89, v89, v92
	v_add_f32_e32 v91, v91, v108
	v_add_f32_e32 v85, v85, v196
	v_add_f32_e32 v87, v87, v198
	v_add_f32_e32 v89, v89, v94
	v_add_f32_e32 v91, v91, v110
	v_add_f32_e32 v85, v85, v87
	v_add_f32_e32 v89, v89, v91
	v_add_f32_e32 v85, v85, v89
	v_add_f32_e32 v175, v175, v85
	s_cmp_eq_u32 s0, s88
	s_cbranch_scc1 .LBB0_651

; #define LAS __attribute__((address_space(3)))
; DI f32x16 zero16() { f32x16 z; for (int i = 0; i < 16; ++i) z[i] = 0.f; return z; }
; #define MFMA32(a, b, c) __builtin_amdgcn_mfma_f32_32x32x16_bf16((a), (b), (c), 0, 0, 0)
; DI void mla_s_softmax(const LAS unsigned char* base, int r, int h, bool is_diag, int lim, const bf16x8 (&qf)[12], f32x16 (&o)[4], float& m_run, float& l_run,
;                       bf16x8 (&pf0)[2], bf16x8 (&pf1)[2]) {
;     f32x16 s0 = zero16(), s1 = zero16();
;     const LAS unsigned char* kp = base + r * MLA_KROW + h * 16;
; #pragma unroll
;     for (int g = 0; g < 3; ++g) {
;         bf16x8 fa[4], fb[4];
; #pragma unroll
;         for (int j = 0; j < 4; ++j) { fa[j] = *(const LAS bf16x8*)(kp + (4 * g + j) * 32); fb[j] = *(const LAS bf16x8*)(kp + 32 * MLA_KROW + (4 * g + j) * 32); }
;         __builtin_amdgcn_sched_barrier(0);
; #pragma unroll
;         for (int j = 0; j < 4; ++j) { s0 = MFMA32(fa[j], qf[4 * g + j], s0); s1 = MFMA32(fb[j], qf[4 * g + j], s1); }
;         __builtin_amdgcn_sched_barrier(0);
;     }
.LBB0_741:
	s_add_i32 s87, s89, 0
	v_add3_u32 v0, s87, v175, v162
	s_andn2_b64 vcc, exec, s[2:3]
	s_branch .Lmla_splain_1
	s_cmp_ge_u32 s77, s73
	s_cbranch_scc1 .Lmla_splain_1
	s_mul_i32 s91, s76, 0xac00
	ds_read_b128 v[2:5], v0
	ds_read_b128 v[6:9], v0 offset:32
	ds_read_b128 v[10:13], v0 offset:12800
	ds_read_b128 v[186:189], v0 offset:12832
	ds_read_b128 v[190:193], v0 offset:64
	ds_read_b128 v[194:197], v0 offset:96
	ds_read_b128 v[198:201], v0 offset:12864
	ds_read_b128 v[202:205], v0 offset:12896
	ds_read_b128 v[206:209], v0 offset:128
	ds_read_b128 v[210:213], v0 offset:160
	ds_read_b128 v[214:217], v0 offset:12928
	ds_read_b128 v[218:221], v0 offset:12960
	ds_read_b128 v[222:225], v0 offset:192
	ds_read_b128 v[226:229], v0 offset:224
	ds_read_b128 v[230:233], v0 offset:12992
	ds_read_b128 v[234:237], v0 offset:13024
	s_waitcnt lgkmcnt(8)
	v_mfma_f32_32x32x16_bf16 v[96:111], v[2:5], v[112:115], 0
	v_readlane_b32 s90, v255, 9
	v_lshl_add_u32 v253, s77, v176, v166
	s_add_i32 m0, s91, s90
	s_nop 0
	global_load_lds_dwordx4 v253, s[12:13]
	v_mfma_f32_32x32x16_bf16 v[80:95], v[10:13], v[112:115], 0
	v_mfma_f32_32x32x16_bf16 v[96:111], v[6:9], v[116:119], v[96:111]
	v_lshl_add_u32 v253, s77, v177, v167
	s_add_i32 m0, s91, s75
	s_nop 0
	global_load_lds_dwordx4 v253, s[12:13]
	v_mfma_f32_32x32x16_bf16 v[80:95], v[186:189], v[116:119], v[80:95]
	v_mfma_f32_32x32x16_bf16 v[96:111], v[190:193], v[120:123], v[96:111]
	v_readlane_b32 s90, v255, 11
	v_lshl_add_u32 v253, s77, v178, v168
	s_add_i32 m0, s91, s90
	s_nop 0
	global_load_lds_dwordx4 v253, s[12:13]
	v_mfma_f32_32x32x16_bf16 v[80:95], v[198:201], v[120:123], v[80:95]
	v_mfma_f32_32x32x16_bf16 v[96:111], v[194:197], v[124:127], v[96:111]
	v_readlane_b32 s90, v255, 49
	v_lshl_add_u32 v253, s77, v179, v169
	s_add_i32 m0, s91, s90
	s_nop 0
	global_load_lds_dwordx4 v253, s[12:13]
	v_mfma_f32_32x32x16_bf16 v[80:95], v[202:205], v[124:127], v[80:95]
	ds_read_b128 v[2:5], v0 offset:256
	ds_read_b128 v[6:9], v0 offset:288
	ds_read_b128 v[10:13], v0 offset:13056
	ds_read_b128 v[186:189], v0 offset:13088
	ds_read_b128 v[190:193], v0 offset:320
	ds_read_b128 v[194:197], v0 offset:352
	ds_read_b128 v[198:201], v0 offset:13120
	ds_read_b128 v[202:205], v0 offset:13152
	s_waitcnt lgkmcnt(8)
	v_mfma_f32_32x32x16_bf16 v[96:111], v[206:209], v[128:131], v[96:111]
	v_lshl_add_u32 v253, s77, v180, v170
	s_add_i32 m0, s91, s86
	s_nop 0
	global_load_lds_dwordx4 v253, s[12:13]
	v_mfma_f32_32x32x16_bf16 v[80:95], v[214:217], v[128:131], v[80:95]
	v_mfma_f32_32x32x16_bf16 v[96:111], v[210:213], v[132:135], v[96:111]
	s_andn2_b64 vcc, exec, s[94:95]
	s_cbranch_vccnz .Lmla_a5_s_1
	v_lshl_add_u32 v253, s77, v181, v171
	s_add_i32 m0, s91, s72
	s_nop 0
	global_load_lds_dwordx4 v253, s[12:13]

; #define LAS __attribute__((address_space(3)))
; DI unsigned pk2(float lo, float hi) { f32x2 v = {lo, hi}; bf2_t r = __builtin_convertvector(v, bf2_t); return __builtin_bit_cast(unsigned, r); }
; #define MFMA32(a, b, c) __builtin_amdgcn_mfma_f32_32x32x16_bf16((a), (b), (c), 0, 0, 0)
; DI void mla_s_softmax(const LAS unsigned char* base, int r, int h, bool is_diag, int lim, const bf16x8 (&qf)[12], f32x16 (&o)[4], float& m_run, float& l_run,
;                       bf16x8 (&pf0)[2], bf16x8 (&pf1)[2]) {
;     ...
;     float ls = 0.f;
; #pragma unroll
;     for (int i = 0; i < 16; ++i) { s0[i] = __builtin_amdgcn_exp2f(s0[i] - m_run); s1[i] = __builtin_amdgcn_exp2f(s1[i] - m_run); ls += s0[i] + s1[i]; }
;     l_run += ls;
; #pragma unroll
;     for (int s = 0; s < 2; ++s) {
;         u32x4 a, c;
;         a.x = pk2(s0[8 * s + 0], s0[8 * s + 1]); a.y = pk2(s0[8 * s + 2], s0[8 * s + 3]); a.z = pk2(s0[8 * s + 4], s0[8 * s + 5]); a.w = pk2(s0[8 * s + 6], s0[8 * s + 7]);
;         c.x = pk2(s1[8 * s + 0], s1[8 * s + 1]); c.y = pk2(s1[8 * s + 2], s1[8 * s + 3]); c.z = pk2(s1[8 * s + 4], s1[8 * s + 5]); c.w = pk2(s1[8 * s + 6], s1[8 * s + 7]);
;         pf0[s] = __builtin_bit_cast(bf16x8, a); pf1[s] = __builtin_bit_cast(bf16x8, c);
;     }
; }
; DI void mla_pv(const LAS unsigned char* base, int r, int h, const bf16x8 (&pf0)[2], const bf16x8 (&pf1)[2], f32x16 (&o)[4]) {
;     const LAS unsigned char* vp = base + MLA_KBYTES + r * MLA_VROW + h * 32;
; #pragma unroll
;     for (int s = 0; s < 2; ++s) {
;         bf16x8 va[4], vb[4];
; #pragma unroll
;         for (int dt = 0; dt < 4; ++dt) { va[dt] = *(const LAS bf16x8*)(vp + dt * 32 * MLA_VROW + s * 16); vb[dt] = *(const LAS bf16x8*)(vp + dt * 32 * MLA_VROW + 64 + s * 16); }
;         __builtin_amdgcn_sched_barrier(0);
; #pragma unroll
;         for (int dt = 0; dt < 4; ++dt) o[dt] = MFMA32(va[dt], pf0[s], o[dt]);
; #pragma unroll
;         for (int dt = 0; dt < 4; ++dt) o[dt] = MFMA32(vb[dt], pf1[s], o[dt]);
;         __builtin_amdgcn_sched_barrier(0);
;     }
.LBB0_745:
	v_sub_f32_e32 v0, v96, v183
	v_exp_f32_e32 v15, v0
	v_sub_f32_e32 v0, v80, v183
	v_sub_f32_e32 v2, v98, v183
	v_exp_f32_e32 v185, v0
	v_sub_f32_e32 v0, v97, v183
	v_exp_f32_e32 v97, v2
	v_sub_f32_e32 v2, v82, v183
	v_exp_f32_e32 v187, v2
	v_sub_f32_e32 v2, v99, v183
	v_exp_f32_e32 v96, v2
	v_sub_f32_e32 v2, v83, v183
	v_exp_f32_e32 v98, v2
	v_sub_f32_e32 v2, v100, v183
	v_exp_f32_e32 v186, v2
	v_sub_f32_e32 v2, v84, v183
	v_exp_f32_e32 v189, v2
	v_sub_f32_e32 v2, v101, v183
	v_exp_f32_e32 v84, v2
	v_sub_f32_e32 v2, v85, v183
	v_exp_f32_e32 v100, v2
	v_sub_f32_e32 v2, v102, v183
	v_exp_f32_e32 v188, v2
	v_sub_f32_e32 v2, v86, v183
	v_exp_f32_e32 v191, v2
	v_sub_f32_e32 v2, v103, v183
	v_exp_f32_e32 v86, v2
	v_sub_f32_e32 v2, v87, v183
	v_exp_f32_e32 v102, v2
	v_sub_f32_e32 v2, v104, v183
	v_exp_f32_e32 v190, v2
	v_sub_f32_e32 v2, v88, v183
	v_exp_f32_e32 v193, v2
	v_sub_f32_e32 v2, v105, v183
	v_exp_f32_e32 v88, v2
	v_sub_f32_e32 v2, v89, v183
	v_exp_f32_e32 v104, v2
	v_sub_f32_e32 v2, v106, v183
	v_exp_f32_e32 v192, v2
	v_sub_f32_e32 v2, v90, v183
	v_exp_f32_e32 v195, v2
	v_sub_f32_e32 v2, v107, v183
	v_exp_f32_e32 v90, v2
	v_sub_f32_e32 v2, v91, v183
	v_exp_f32_e32 v106, v2
	v_sub_f32_e32 v2, v108, v183
	v_exp_f32_e32 v194, v2
	v_sub_f32_e32 v2, v92, v183
	v_exp_f32_e32 v197, v2
	v_sub_f32_e32 v2, v109, v183
	v_exp_f32_e32 v92, v2
	v_sub_f32_e32 v2, v93, v183
	v_exp_f32_e32 v108, v2
	v_sub_f32_e32 v2, v110, v183
	v_exp_f32_e32 v196, v2
	v_sub_f32_e32 v2, v94, v183
	v_exp_f32_e32 v198, v2
	v_sub_f32_e32 v2, v111, v183
	v_exp_f32_e32 v14, v0
	v_sub_f32_e32 v0, v81, v183
	v_exp_f32_e32 v94, v2
	v_sub_f32_e32 v2, v95, v183
	v_exp_f32_e32 v0, v0
	v_exp_f32_e32 v110, v2
	v_cvt_pk_bf16_f32 v80, v15, v14
	v_cvt_pk_bf16_f32 v81, v97, v96
	v_cvt_pk_bf16_f32 v82, v186, v84
	v_cvt_pk_bf16_f32 v83, v188, v86
	v_cvt_pk_bf16_f32 v6, v185, v0
	v_cvt_pk_bf16_f32 v7, v187, v98
	v_cvt_pk_bf16_f32 v8, v189, v100
	v_cvt_pk_bf16_f32 v9, v191, v102
	v_cvt_pk_bf16_f32 v10, v190, v88
	v_cvt_pk_bf16_f32 v11, v192, v90
	v_cvt_pk_bf16_f32 v12, v194, v92
	v_cvt_pk_bf16_f32 v13, v196, v94
	v_cvt_pk_bf16_f32 v2, v193, v104
	v_cvt_pk_bf16_f32 v3, v195, v106
	v_cvt_pk_bf16_f32 v4, v197, v108
	s_andn2_b64 vcc, exec, s[2:3]
	v_cvt_pk_bf16_f32 v5, v198, v110
	s_cbranch_vccnz .LBB0_747
	s_cmp_ge_u32 s77, s73
	s_cbranch_scc1 .Lmla_epv_plain_1
	s_mul_i32 s91, s76, 0xac00
	s_waitcnt lgkmcnt(0)
	v_mfma_f32_32x32x16_bf16 v[64:79], v[200:203], v[80:83], v[64:79]
	v_readlane_b32 s90, v255, 9
	v_lshl_add_u32 v253, s77, v176, v166
	s_add_i32 m0, s91, s90
	s_nop 0
	global_load_lds_dwordx4 v253, s[12:13]
	v_mfma_f32_32x32x16_bf16 v[48:63], v[208:211], v[80:83], v[48:63]
	v_mfma_f32_32x32x16_bf16 v[32:47], v[216:219], v[80:83], v[32:47]
	v_lshl_add_u32 v253, s77, v177, v167
	s_add_i32 m0, s91, s75
	s_nop 0
	global_load_lds_dwordx4 v253, s[12:13]
	v_mfma_f32_32x32x16_bf16 v[16:31], v[224:227], v[80:83], v[16:31]
	v_mfma_f32_32x32x16_bf16 v[64:79], v[204:207], v[6:9], v[64:79]
	v_readlane_b32 s90, v255, 11
	v_lshl_add_u32 v253, s77, v178, v168
	s_add_i32 m0, s91, s90
	s_nop 0
	global_load_lds_dwordx4 v253, s[12:13]
	v_mfma_f32_32x32x16_bf16 v[48:63], v[212:215], v[6:9], v[48:63]
	v_mfma_f32_32x32x16_bf16 v[32:47], v[220:223], v[6:9], v[32:47]
	v_readlane_b32 s90, v255, 49
	v_lshl_add_u32 v253, s77, v179, v169
	s_add_i32 m0, s91, s90
	s_nop 0
	global_load_lds_dwordx4 v253, s[12:13]
	v_mfma_f32_32x32x16_bf16 v[16:31], v[228:231], v[6:9], v[16:31]
	ds_read_b128 v[200:203], v252 offset:30288
	ds_read_b128 v[204:207], v252 offset:34896
	ds_read_b128 v[208:211], v252 offset:39504
	v_mfma_f32_32x32x16_bf16 v[64:79], v[232:235], v[10:13], v[64:79]
	v_lshl_add_u32 v253, s77, v180, v170
	s_add_i32 m0, s91, s86
	s_nop 0
	global_load_lds_dwordx4 v253, s[12:13]
	v_mfma_f32_32x32x16_bf16 v[48:63], v[236:239], v[10:13], v[48:63]
	v_mfma_f32_32x32x16_bf16 v[32:47], v[240:243], v[10:13], v[32:47]
	s_andn2_b64 vcc, exec, s[94:95]
	s_cbranch_vccnz .Lmla_a5_epv_1
	v_lshl_add_u32 v253, s77, v181, v171
	s_add_i32 m0, s91, s72
	s_nop 0
	global_load_lds_dwordx4 v253, s[12:13]

; DI void mla_s_softmax(const LAS unsigned char* base, int r, int h, bool is_diag, int lim, const bf16x8 (&qf)[12], f32x16 (&o)[4], float& m_run, float& l_run,
;                       bf16x8 (&pf0)[2], bf16x8 (&pf1)[2]) {
;     ...
;     float ls = 0.f;
; #pragma unroll
;     for (int i = 0; i < 16; ++i) { s0[i] = __builtin_amdgcn_exp2f(s0[i] - m_run); s1[i] = __builtin_amdgcn_exp2f(s1[i] - m_run); ls += s0[i] + s1[i]; }
;     l_run += ls;
.LBB0_747:
	v_add_f32_e32 v85, v15, v185
	v_add_f32_e32 v87, v14, v0
	v_add_f32_e32 v89, v97, v187
	v_add_f32_e32 v91, v96, v98
	v_add_f32_e32 v85, v85, v186
	v_add_f32_e32 v87, v87, v189
	v_add_f32_e32 v89, v89, v84
	v_add_f32_e32 v91, v91, v100
	v_add_f32_e32 v85, v85, v188
	v_add_f32_e32 v87, v87, v191
	v_add_f32_e32 v89, v89, v86
	v_add_f32_e32 v91, v91, v102
	v_add_f32_e32 v85, v85, v190
	v_add_f32_e32 v87, v87, v193
	v_add_f32_e32 v89, v89, v88
	v_add_f32_e32 v91, v91, v104
	v_add_f32_e32 v85, v85, v192
	v_add_f32_e32 v87, v87, v195
	v_add_f32_e32 v89, v89, v90
	v_add_f32_e32 v91, v91, v106
	v_add_f32_e32 v85, v85, v194
	v_add_f32_e32 v87, v87, v197
	v_add_f32_e32 v89, v89, v92
	v_add_f32_e32 v91, v91, v108
	v_add_f32_e32 v85, v85, v196
	v_add_f32_e32 v87, v87, v198
	v_add_f32_e32 v89, v89, v94
	v_add_f32_e32 v91, v91, v110
	v_add_f32_e32 v85, v85, v87
	v_add_f32_e32 v89, v89, v91
	v_add_f32_e32 v85, v85, v89
	v_add_f32_e32 v172, v172, v85
	s_cmp_eq_u32 s73, s77
	s_cbranch_scc1 .LBB0_753
